# half-K-tile stagger between odd and even row-block workgroups at the entry of the FFN-up GEMMs (P2, P11)
# speedup vs baseline: 1.0264x; 1.0264x over previous
; #define PG8_STAGE(bufoff, gbase, voff) do { _Pragma("unroll") for (int _i = 0; _i < 2; ++_i) \
;         __builtin_amdgcn_global_load_lds((const unsigned*)((const char*)(gbase) + (voff)[_i]), (PG8_LAS unsigned*)(lds + (bufoff) + ldsw + _i * 8192), 16, 0, 0); } while (0)
; #define PG8_WAIT_V(n) asm volatile("s_waitcnt vmcnt(" #n ")" ::: "memory")
; #define PG8_BAR __builtin_amdgcn_s_barrier()
; template <class Epi, class Sched, bool ALIGN_EPI = false, bool SP2 = false>
; __device__ __forceinline__ void gemm_phase(PG8_LAS unsigned char* lds, const Gemm g, const Sched& S, const Epi& E, const int wid) {
;     ...
;     const char* cA = (const char*)g.A + (size_t)cur.pm * tstep; const char* cB = (const char*)g.Bt + (size_t)cur.pn * tstep;
;     S.a_ready(cur);
;     if constexpr (SP2) {
;         PG8_STAGE(PG8_SB(0, 0), cB, voffB); PG8_STAGE(PG8_SB(0, 1), cB + hstep, voffB); PG8_STAGE(PG8_SA(0, 0), cA, voffA); PG8_STAGE(PG8_SA(0, 1), cA + hstep, voffA);
;         if (wr == 1) PG8_BAR;
;         PG8_WAIT_V(2); PG8_BAR;
.LBB0_141:
	s_bitcmp1_b32 s82, 3
	s_cbranch_scc0 .Lgst141
	s_sleep 27
